# baseline (speedup 1.0000x reference)
; __device__ __forceinline__ void evenmix_phase(const Params& p, int e, int rev) {
;     ...
;     } else {
;       const int pc = 2 * (tid - 256);
;       const int g = pc >> 7;
;       const int w = 2 << g;
;       float Sa = 0.f, Sb = 0.f;
;       uint32_t V[2][8], VO[2][8];
;     ...
;       EP_LOAD(0, 0);
.LBB0_525:
	s_sub_i32 s10, 0xff, s20
	s_and_b64 s[8:9], s[6:7], exec
	s_cselect_b32 s10, s20, s10
	s_ashr_i32 s11, s10, 31
	s_lshl_b64 s[8:9], s[10:11], 8
	s_and_b32 s21, s8, 0xf00
	s_and_saveexec_b64 s[12:13], s[2:3]
	s_xor_b64 s[12:13], exec, s[12:13]
	s_cbranch_execz .LBB0_538
	v_sub_u32_e32 v26, s21, v34
	v_cmp_lt_i32_e32 vcc, -2, v26
	s_lshl_b64 s[14:15], s[10:11], 20
	v_readlane_b32 s16, v252, 51
	v_cndmask_b32_e32 v24, 0, v35, vcc
	v_ashrrev_i32_e32 v25, 31, v24
	v_readlane_b32 s17, v252, 52
	s_add_u32 s16, s16, s14
	v_lshl_add_u64 v[24:25], s[8:9], 0, v[24:25]
	s_addc_u32 s17, s17, s15
	v_lshlrev_b64 v[24:25], 12, v[24:25]
	v_lshl_add_u64 v[22:23], v[2:3], 1, s[16:17]
	v_lshl_add_u64 v[24:25], v[16:17], 0, v[24:25]
	global_load_dword v27, v[22:23], off offset:3072
	global_load_dword v28, v[24:25], off offset:3072
	v_add_co_u32_e32 v24, vcc, s41, v22
	s_movk_i32 s16, 0x3000
	s_nop 0
	v_addc_co_u32_e32 v25, vcc, 0, v23, vcc
	v_cmp_lt_i32_e32 vcc, -3, v26
	global_load_dword v29, v[24:25], off offset:3072
	v_mov_b32_e32 v152, v153
	v_cndmask_b32_e32 v24, 1, v36, vcc
	v_ashrrev_i32_e32 v25, 31, v24
	v_lshl_add_u64 v[24:25], s[8:9], 0, v[24:25]
	v_lshlrev_b64 v[24:25], 12, v[24:25]
	v_lshl_add_u64 v[24:25], v[16:17], 0, v[24:25]
	global_load_dword v30, v[24:25], off offset:3072
	v_add_co_u32_e32 v24, vcc, s33, v22
	s_nop 1
	v_addc_co_u32_e32 v25, vcc, 0, v23, vcc
	global_load_dword v31, v[24:25], off offset:3072
	v_add_u32_e32 v24, 2, v26
	v_cmp_lt_i32_e32 vcc, -2, v24
	s_nop 1
	v_cndmask_b32_e32 v24, 2, v37, vcc
	v_ashrrev_i32_e32 v25, 31, v24
	v_lshl_add_u64 v[24:25], s[8:9], 0, v[24:25]
	v_lshlrev_b64 v[24:25], 12, v[24:25]
	v_lshl_add_u64 v[24:25], v[16:17], 0, v[24:25]
	global_load_dword v32, v[24:25], off offset:3072
	v_add_co_u32_e32 v24, vcc, s16, v22
	s_movk_i32 s16, 0x5000
	s_nop 0
	v_addc_co_u32_e32 v25, vcc, 0, v23, vcc
	global_load_dword v33, v[24:25], off offset:3072
	v_add_u32_e32 v24, 3, v26
	v_cmp_lt_i32_e32 vcc, -2, v24
	s_nop 1
	v_cndmask_b32_e32 v24, 3, v38, vcc
	v_ashrrev_i32_e32 v25, 31, v24
	v_lshl_add_u64 v[24:25], s[8:9], 0, v[24:25]
	v_lshlrev_b64 v[24:25], 12, v[24:25]
	v_lshl_add_u64 v[24:25], v[16:17], 0, v[24:25]
	global_load_dword v44, v[24:25], off offset:3072
	v_add_co_u32_e32 v24, vcc, s58, v22
	s_nop 1
	v_addc_co_u32_e32 v25, vcc, 0, v23, vcc
	global_load_dword v45, v[24:25], off offset:3072
	v_add_u32_e32 v24, 4, v26
	v_cmp_lt_i32_e32 vcc, -2, v24
	s_nop 1
	v_cndmask_b32_e32 v24, 4, v39, vcc
	v_ashrrev_i32_e32 v25, 31, v24
	v_lshl_add_u64 v[24:25], s[8:9], 0, v[24:25]
	v_lshlrev_b64 v[24:25], 12, v[24:25]
	v_lshl_add_u64 v[24:25], v[16:17], 0, v[24:25]
	global_load_dword v46, v[24:25], off offset:3072
	v_add_co_u32_e32 v24, vcc, s16, v22
	s_movk_i32 s16, 0x6000
	s_nop 0
	v_addc_co_u32_e32 v25, vcc, 0, v23, vcc
	global_load_dword v47, v[24:25], off offset:3072
	v_add_u32_e32 v24, 5, v26
	v_cmp_lt_i32_e32 vcc, -2, v24
	s_nop 1
	v_cndmask_b32_e32 v24, 5, v40, vcc
	v_ashrrev_i32_e32 v25, 31, v24
	v_lshl_add_u64 v[24:25], s[8:9], 0, v[24:25]
	v_lshlrev_b64 v[24:25], 12, v[24:25]
	v_lshl_add_u64 v[24:25], v[16:17], 0, v[24:25]
	global_load_dword v48, v[24:25], off offset:3072
	v_add_co_u32_e32 v24, vcc, s16, v22
	s_movk_i32 s16, 0x7000
	s_nop 0
	v_addc_co_u32_e32 v25, vcc, 0, v23, vcc
	global_load_dword v49, v[24:25], off offset:3072
	v_add_u32_e32 v24, 6, v26
	v_cmp_lt_i32_e32 vcc, -2, v24
	s_nop 1
	v_cndmask_b32_e32 v24, 6, v41, vcc
	v_ashrrev_i32_e32 v25, 31, v24
	v_lshl_add_u64 v[24:25], s[8:9], 0, v[24:25]
	v_lshlrev_b64 v[24:25], 12, v[24:25]
	v_add_co_u32_e32 v22, vcc, s16, v22
	v_lshl_add_u64 v[24:25], v[16:17], 0, v[24:25]
	s_nop 0
	v_addc_co_u32_e32 v23, vcc, 0, v23, vcc
	global_load_dword v50, v[24:25], off offset:3072
	global_load_dword v51, v[22:23], off offset:3072
	v_add_u32_e32 v22, 7, v26
	v_cmp_lt_i32_e32 vcc, -2, v22
	v_mov_b64_e32 v[24:25], v[152:153]
	s_nop 0
	v_cndmask_b32_e32 v22, 7, v42, vcc
	v_ashrrev_i32_e32 v23, 31, v22
	v_lshl_add_u64 v[22:23], s[8:9], 0, v[22:23]
	v_lshlrev_b64 v[22:23], 12, v[22:23]
	v_lshl_add_u64 v[22:23], v[16:17], 0, v[22:23]
	global_load_dword v61, v[22:23], off offset:3072
	s_and_saveexec_b64 s[16:17], s[4:5]
	s_cbranch_execz .LBB0_532
; __device__ __forceinline__ float bf2f(bf16 h) { return __uint_as_float(((uint32_t)h) << 16); }
; __device__ __forceinline__ void evenmix_phase(const Params& p, int e, int rev) {
;     ...
;       for (int k = 1; k < w; ++k) {
;         if (t0 - k >= 0) {
;           const uint32_t vv = *(const uint32_t*)(u + (tok0 - k) * 2048 + 1536 + pc);
;           Sa += bf2f((bf16)(vv & 0xffff));
;           Sb += bf2f((bf16)(vv >> 16));
;         }
;       }
	v_mov_b32_e32 v152, v153
	v_lshl_add_u64 v[22:23], v[20:21], 0, s[14:15]
	v_mov_b64_e32 v[24:25], v[152:153]
	s_cmp_eq_u32 s21, 0
	s_cbranch_scc1 .Lhalo_done
	s_movk_i32 s24, 0xf000
	s_mov_b32 s25, -1
	global_load_dword v104, v[22:23], off
	v_lshl_add_u64 v[22:23], v[22:23], 0, s[24:25]
	global_load_dword v105, v[22:23], off
	v_lshl_add_u64 v[22:23], v[22:23], 0, s[24:25]
	global_load_dword v106, v[22:23], off
	v_lshl_add_u64 v[22:23], v[22:23], 0, s[24:25]
	global_load_dword v107, v[22:23], off
	v_lshl_add_u64 v[22:23], v[22:23], 0, s[24:25]
	global_load_dword v108, v[22:23], off
	v_lshl_add_u64 v[22:23], v[22:23], 0, s[24:25]
	global_load_dword v109, v[22:23], off
	v_lshl_add_u64 v[22:23], v[22:23], 0, s[24:25]
	global_load_dword v110, v[22:23], off
	v_lshl_add_u64 v[22:23], v[22:23], 0, s[24:25]
	global_load_dword v111, v[22:23], off
	v_lshl_add_u64 v[22:23], v[22:23], 0, s[24:25]
	global_load_dword v112, v[22:23], off
	v_lshl_add_u64 v[22:23], v[22:23], 0, s[24:25]
	global_load_dword v113, v[22:23], off
	v_lshl_add_u64 v[22:23], v[22:23], 0, s[24:25]
	global_load_dword v114, v[22:23], off
	v_lshl_add_u64 v[22:23], v[22:23], 0, s[24:25]
	global_load_dword v115, v[22:23], off
	v_lshl_add_u64 v[22:23], v[22:23], 0, s[24:25]
	global_load_dword v116, v[22:23], off
	v_lshl_add_u64 v[22:23], v[22:23], 0, s[24:25]
	global_load_dword v117, v[22:23], off
	v_lshl_add_u64 v[22:23], v[22:23], 0, s[24:25]
	global_load_dword v118, v[22:23], off
	v_readfirstlane_b32 s22, v34
	s_waitcnt vmcnt(0)
	v_lshlrev_b32_e32 v52, 16, v104
	v_and_b32_e32 v53, 0xffff0000, v104
	v_pk_add_f32 v[24:25], v[24:25], v[52:53]
	s_cmp_le_u32 s22, 2
	s_cbranch_scc1 .Lhalo_done
	v_lshlrev_b32_e32 v52, 16, v105
	v_and_b32_e32 v53, 0xffff0000, v105
	v_pk_add_f32 v[24:25], v[24:25], v[52:53]
	v_lshlrev_b32_e32 v52, 16, v106
	v_and_b32_e32 v53, 0xffff0000, v106
	v_pk_add_f32 v[24:25], v[24:25], v[52:53]
	s_cmp_le_u32 s22, 4
	s_cbranch_scc1 .Lhalo_done
	v_lshlrev_b32_e32 v52, 16, v107
	v_and_b32_e32 v53, 0xffff0000, v107
	v_pk_add_f32 v[24:25], v[24:25], v[52:53]
	v_lshlrev_b32_e32 v52, 16, v108
	v_and_b32_e32 v53, 0xffff0000, v108
	v_pk_add_f32 v[24:25], v[24:25], v[52:53]
	v_lshlrev_b32_e32 v52, 16, v109
	v_and_b32_e32 v53, 0xffff0000, v109
	v_pk_add_f32 v[24:25], v[24:25], v[52:53]
	v_lshlrev_b32_e32 v52, 16, v110
	v_and_b32_e32 v53, 0xffff0000, v110
	v_pk_add_f32 v[24:25], v[24:25], v[52:53]
	s_cmp_le_u32 s22, 8
	s_cbranch_scc1 .Lhalo_done
	v_lshlrev_b32_e32 v52, 16, v111
	v_and_b32_e32 v53, 0xffff0000, v111
	v_pk_add_f32 v[24:25], v[24:25], v[52:53]
	v_lshlrev_b32_e32 v52, 16, v112
	v_and_b32_e32 v53, 0xffff0000, v112
	v_pk_add_f32 v[24:25], v[24:25], v[52:53]
	v_lshlrev_b32_e32 v52, 16, v113
	v_and_b32_e32 v53, 0xffff0000, v113
	v_pk_add_f32 v[24:25], v[24:25], v[52:53]
	v_lshlrev_b32_e32 v52, 16, v114
	v_and_b32_e32 v53, 0xffff0000, v114
	v_pk_add_f32 v[24:25], v[24:25], v[52:53]
	v_lshlrev_b32_e32 v52, 16, v115
	v_and_b32_e32 v53, 0xffff0000, v115
	v_pk_add_f32 v[24:25], v[24:25], v[52:53]
	v_lshlrev_b32_e32 v52, 16, v116
	v_and_b32_e32 v53, 0xffff0000, v116
	v_pk_add_f32 v[24:25], v[24:25], v[52:53]
	v_lshlrev_b32_e32 v52, 16, v117
	v_and_b32_e32 v53, 0xffff0000, v117
	v_pk_add_f32 v[24:25], v[24:25], v[52:53]
	v_lshlrev_b32_e32 v52, 16, v118
	v_and_b32_e32 v53, 0xffff0000, v118
	v_pk_add_f32 v[24:25], v[24:25], v[52:53]
.Lhalo_done:
.LBB0_532:
	s_or_b64 exec, exec, s[16:17]
	v_readlane_b32 s72, v253, 22
	v_readlane_b32 s86, v253, 36
	v_readlane_b32 s87, v253, 37
	s_add_u32 s14, s86, s14
	s_addc_u32 s15, s87, s15
	s_lshl_b64 s[16:17], s[10:11], 19
	s_add_u32 s16, s86, s16
	s_addc_u32 s17, s87, s17
	s_mov_b32 s22, -2
	s_mov_b32 s24, 0
	v_readlane_b32 s73, v253, 23
	v_readlane_b32 s74, v253, 24
	v_readlane_b32 s75, v253, 25
	v_readlane_b32 s76, v253, 26
	v_readlane_b32 s77, v253, 27
	v_readlane_b32 s78, v253, 28
	v_readlane_b32 s79, v253, 29
	v_readlane_b32 s80, v253, 30
	v_readlane_b32 s81, v253, 31
	v_readlane_b32 s82, v253, 32
	v_readlane_b32 s83, v253, 33
	v_readlane_b32 s84, v253, 34
	v_readlane_b32 s85, v253, 35
	s_branch .LBB0_534
